# scan R1: all 12 fragment reads hoisted above the next-chunk global-load block; second product reuses A fragments (no re-read)
# baseline (speedup 1.0000x reference)
.LBB0_577:
	s_or_b64 exec, exec, s[36:37]
	ds_read_b128 v[48:51], v137
	v_mov_b32_e32 v36, 0
	v_mov_b32_e32 v40, 0
	v_mov_b32_e32 v41, 0
	v_mov_b32_e32 v42, 0
	v_mov_b32_e32 v43, 0
	s_and_saveexec_b64 s[36:37], s[44:45]
	ds_read_b128 v[40:43], v143
	s_or_b64 exec, exec, s[36:37]
	ds_read_b128 v[44:47], v137 offset:16
	v_mov_b32_e32 v37, 0
	v_mov_b32_e32 v38, 0
	v_mov_b32_e32 v39, 0
	s_and_saveexec_b64 s[36:37], s[44:45]
	ds_read_b128 v[36:39], v157
	s_or_b64 exec, exec, s[36:37]
	s_waitcnt lgkmcnt(1)
	v_mul_f32_e32 v48, 0x3fb8aa3b, v48
	v_exp_f32_e32 v48, v48
	s_and_saveexec_b64 s[36:37], s[46:47]
	ds_write_b32 v148, v48
	s_or_b64 exec, exec, s[36:37]
	v_mul_f32_e32 v49, 0x3fb8aa3b, v49
	v_exp_f32_e32 v49, v49
	s_and_saveexec_b64 s[36:37], s[46:47]
	ds_write_b32 v148, v49 offset:4
	s_or_b64 exec, exec, s[36:37]
	v_mul_f32_e32 v50, 0x3fb8aa3b, v50
	v_exp_f32_e32 v50, v50
	s_and_saveexec_b64 s[36:37], s[46:47]
	ds_write_b32 v148, v50 offset:8
	s_or_b64 exec, exec, s[36:37]
	v_mul_f32_e32 v51, 0x3fb8aa3b, v51
	v_exp_f32_e32 v51, v51
	s_and_saveexec_b64 s[36:37], s[46:47]
	ds_write_b32 v148, v51 offset:12
	s_or_b64 exec, exec, s[36:37]
	s_waitcnt lgkmcnt(0)
	v_mul_f32_e32 v44, 0x3fb8aa3b, v44
	v_exp_f32_e32 v244, v44
	s_and_saveexec_b64 s[36:37], s[46:47]
	ds_write_b32 v148, v244 offset:16
	s_or_b64 exec, exec, s[36:37]
	v_mul_f32_e32 v44, 0x3fb8aa3b, v45
	v_exp_f32_e32 v45, v44
	s_and_saveexec_b64 s[36:37], s[46:47]
	ds_write_b32 v148, v45 offset:20
	s_or_b64 exec, exec, s[36:37]
	v_mul_f32_e32 v44, 0x3fb8aa3b, v46
	v_exp_f32_e32 v46, v44
	s_and_saveexec_b64 s[36:37], s[46:47]
	ds_write_b32 v148, v46 offset:24
	s_or_b64 exec, exec, s[36:37]
	v_mul_f32_e32 v44, 0x3fb8aa3b, v47
	v_exp_f32_e32 v44, v44
	s_and_saveexec_b64 s[36:37], s[46:47]
	ds_write_b32 v148, v44 offset:28
	s_or_b64 exec, exec, s[36:37]
	v_add_f32_e32 v47, v242, v243
	v_max_f32_e32 v47, 0x2b8cbccc, v47
	v_rsq_f32_e32 v242, v47
	v_mul_f32_e32 v40, 0x3fb8aa3b, v40
	v_exp_f32_e32 v40, v40
	v_rcp_f32_e32 v47, v48
	v_mul_f32_e32 v241, v241, v242
	v_mul_f32_e32 v36, 0x3fb8aa3b, v36
	v_mul_f32_e32 v243, v241, v40
	v_mul_f32_e32 v40, v241, v227
	v_mul_f32_e32 v227, v40, v47
	v_mul_f32_e32 v40, 0x3fb8aa3b, v41
	v_exp_f32_e32 v40, v40
	v_rcp_f32_e32 v41, v49
	v_mul_f32_e32 v237, v237, v47
	v_mul_f32_e32 v47, v239, v242
	v_mul_f32_e32 v239, v47, v40
	v_mul_f32_e32 v40, v47, v226
	v_mul_f32_e32 v226, v40, v41
	v_mul_f32_e32 v40, 0x3fb8aa3b, v42
	v_exp_f32_e32 v40, v40
	v_mul_f32_e32 v235, v235, v41
	v_rcp_f32_e32 v41, v50
	v_mul_f32_e32 v42, v240, v242
	v_mul_f32_e32 v240, v42, v40
	v_mul_f32_e32 v40, v42, v214
	v_mul_f32_e32 v50, v120, v50
	v_mul_f32_e32 v120, v40, v41
	v_mul_f32_e32 v40, 0x3fb8aa3b, v43
	v_exp_f32_e32 v40, v40
	v_mul_f32_e32 v214, v233, v41
	v_rcp_f32_e32 v41, v51
	v_mul_f32_e32 v42, v238, v242
	v_mul_f32_e32 v233, v42, v40
	v_mul_f32_e32 v40, v42, v213
	v_exp_f32_e32 v36, v36
	v_mul_f32_e32 v51, v121, v51
	v_mul_f32_e32 v121, v40, v41
	v_rcp_f32_e32 v40, v244
	v_mul_f32_e32 v213, v230, v41
	v_mul_f32_e32 v41, v236, v242
	v_mul_f32_e32 v230, v41, v36
	v_mul_f32_e32 v36, v41, v212
	v_mul_f32_e32 v212, v36, v40
	v_mul_f32_e32 v36, 0x3fb8aa3b, v37
	v_exp_f32_e32 v36, v36
	v_rcp_f32_e32 v37, v45
	v_mul_f32_e32 v229, v229, v40
	v_mul_f32_e32 v40, v234, v242
	v_mul_f32_e32 v234, v40, v36
	v_mul_f32_e32 v36, v40, v211
	v_mul_f32_e32 v211, v36, v37
	v_mul_f32_e32 v36, 0x3fb8aa3b, v38
	v_exp_f32_e32 v36, v36
	v_mul_f32_e32 v228, v228, v37
	v_rcp_f32_e32 v37, v46
	v_mul_f32_e32 v39, 0x3fb8aa3b, v39
	v_exp_f32_e32 v39, v39
	v_mul_f32_e32 v38, v231, v242
	v_mul_f32_e32 v236, v2, v46
	v_mul_f32_e32 v2, v38, v210
	v_mul_f32_e32 v122, v122, v48
	v_mul_f32_e32 v123, v123, v49
	v_mul_f32_e32 v125, v125, v45
	v_mul_f32_e32 v231, v38, v36
	v_mul_f32_e32 v210, v2, v37
	v_mul_f32_e32 v232, v232, v37
	v_lshlrev_b32_e32 v36, 16, v76
	v_and_b32_e32 v37, 0xffff0000, v76
	v_lshlrev_b32_e32 v40, 16, v77
	v_and_b32_e32 v41, 0xffff0000, v77
	v_lshlrev_b32_e32 v2, 16, v80
	v_and_b32_e32 v38, 0xffff0000, v80
	v_lshlrev_b32_e32 v45, 16, v81
	v_and_b32_e32 v48, 0xffff0000, v81
	v_lshlrev_b32_e32 v42, 16, v78
	v_and_b32_e32 v43, 0xffff0000, v78
	v_lshlrev_b32_e32 v46, 16, v79
	v_and_b32_e32 v47, 0xffff0000, v79
	v_lshlrev_b32_e32 v49, 16, v82
	v_and_b32_e32 v246, 0xffff0000, v82
	v_lshlrev_b32_e32 v247, 16, v83
	v_and_b32_e32 v248, 0xffff0000, v83
	v_rcp_f32_e32 v224, v44
	v_mul_f32_e32 v215, v215, v242
	v_mul_f32_e32 v124, v124, v244
	v_lshlrev_b32_e32 v238, 16, v84
	v_and_b32_e32 v241, 0xffff0000, v84
	v_lshlrev_b32_e32 v244, 16, v85
	v_and_b32_e32 v245, 0xffff0000, v85
	v_lshlrev_b32_e32 v249, 16, v86
	v_and_b32_e32 v250, 0xffff0000, v86
	v_lshlrev_b32_e32 v251, 16, v87
	v_and_b32_e32 v216, 0xffff0000, v87
	v_mul_f32_e32 v242, v215, v39
	v_mul_f32_e32 v222, v3, v44
	v_sub_f32_e32 v3, v38, v37
	v_sub_f32_e32 v2, v2, v36
	v_sub_f32_e32 v39, v48, v41
	v_sub_f32_e32 v38, v45, v40
	v_sub_f32_e32 v45, v246, v43
	v_sub_f32_e32 v44, v49, v42
	v_sub_f32_e32 v49, v248, v47
	v_sub_f32_e32 v48, v247, v46
	v_pk_fma_f32 v[34:35], v[48:49], v[34:35], v[46:47]
	v_pk_fma_f32 v[32:33], v[44:45], v[32:33], v[42:43]
	v_pk_fma_f32 v[30:31], v[38:39], v[30:31], v[40:41]
	v_pk_fma_f32 v[2:3], v[2:3], v[28:29], v[36:37]
	v_sub_f32_e32 v29, v216, v47
	v_sub_f32_e32 v28, v251, v46
	v_sub_f32_e32 v39, v250, v43
	v_sub_f32_e32 v38, v249, v42
	v_sub_f32_e32 v41, v245, v41
	v_sub_f32_e32 v40, v244, v40
	v_sub_f32_e32 v37, v241, v37
	v_sub_f32_e32 v36, v238, v36
	v_mul_f32_e32 v1, v215, v1
	v_pk_fma_f32 v[2:3], v[36:37], v[24:25], v[2:3]
	v_pk_fma_f32 v[24:25], v[40:41], v[26:27], v[30:31]
	v_pk_fma_f32 v[26:27], v[38:39], v[20:21], v[32:33]
	v_pk_fma_f32 v[28:29], v[28:29], v[22:23], v[34:35]
	v_cvt_pk_bf16_f32 v23, v231, v242
	v_cvt_pk_bf16_f32 v22, v230, v234
	v_cvt_pk_bf16_f32 v21, v240, v233
	v_cvt_pk_bf16_f32 v20, v243, v239
	v_mul_f32_e32 v1, v1, v224
	ds_write_b128 v200, v[20:23]
	v_cvt_pk_bf16_f32 v23, v236, v222
	v_cvt_pk_bf16_f32 v22, v124, v125
	v_cvt_pk_bf16_f32 v21, v50, v51
	v_cvt_pk_bf16_f32 v20, v122, v123
	v_mul_f32_e32 v215, v225, v224
	ds_write_b128 v200, v[20:23] offset:9216
	v_cvt_pk_bf16_f32 v23, v210, v1
	v_cvt_pk_bf16_f32 v22, v212, v211
	v_cvt_pk_bf16_f32 v21, v120, v121
	v_cvt_pk_bf16_f32 v20, v227, v226
	ds_write_b128 v200, v[20:23] offset:18432
	v_cvt_pk_bf16_f32 v23, v232, v215
	v_cvt_pk_bf16_f32 v22, v229, v228
	v_cvt_pk_bf16_f32 v21, v214, v213
	v_cvt_pk_bf16_f32 v20, v237, v235
	ds_write_b128 v200, v[20:23] offset:27648
	v_cvt_pk_bf16_f32 v23, v28, v29
	v_cvt_pk_bf16_f32 v22, v26, v27
	v_cvt_pk_bf16_f32 v21, v24, v25
	v_cvt_pk_bf16_f32 v20, v2, v3
	s_cmpk_eq_i32 s49, 0x7c0
	ds_write_b128 v200, v[20:23] offset:36864
	s_waitcnt lgkmcnt(0)
	s_barrier
	v_add_u32_e32 v242, v149, v175
	ds_read_b128 v[226:229], v194
	ds_read_b128 v[36:39], v201
	ds_read_b128 v[230:233], v194 offset:32
	ds_read_b128 v[40:43], v201 offset:32
	ds_read_b128 v[234:237], v194 offset:64
	ds_read_b128 v[44:47], v201 offset:64
	ds_read_b128 v[238:241], v194 offset:96
	ds_read_b128 v[48:51], v201 offset:96
	ds_read_b128 v[120:123], v242
	ds_read_b128 v[210:213], v242 offset:32
	ds_read_b128 v[244:247], v242 offset:64
	ds_read_b128 v[248:251], v242 offset:96
	s_cbranch_scc1 .LBB0_611
	v_add3_u32 v1, v127, s49, 64
	v_cndmask_b32_e64 v1, v204, v1, s[34:35]
	v_add_u32_e32 v22, s48, v1
	s_movk_i32 s36, 0x6000
	v_mad_i64_i32 v[20:21], s[36:37], v22, s36, v[114:115]
	global_load_dwordx4 v[52:55], v[20:21], off
	v_mov_b32_e32 v58, v0
	v_mov_b32_e32 v59, v0
	v_mov_b32_e32 v56, v0
	v_mov_b32_e32 v57, v0
	v_mov_b64_e32 v[62:63], v[58:59]
	v_cmp_lt_i32_e64 s[36:37], 0, v1
	v_mov_b64_e32 v[60:61], v[56:57]
	s_and_saveexec_b64 s[38:39], s[36:37]
	s_cbranch_execz .LBB0_600
	v_add_co_u32_e32 v2, vcc, 0xffffa000, v20
	s_nop 1
	v_addc_co_u32_e32 v3, vcc, -1, v21, vcc
	global_load_dwordx4 v[60:63], v[2:3], off

.LBB0_611:
	s_waitcnt lgkmcnt(10)
	v_mfma_f32_32x32x16_bf16 v[20:35], v[226:229], v[36:39], 0
	s_andn2_b64 vcc, exec, s[40:41]
	s_waitcnt lgkmcnt(8)
	v_mfma_f32_32x32x16_bf16 v[20:35], v[230:233], v[40:43], v[20:35]
	s_waitcnt lgkmcnt(6)
	v_mfma_f32_32x32x16_bf16 v[20:35], v[234:237], v[44:47], v[20:35]
	s_waitcnt lgkmcnt(0)
	v_mfma_f32_32x32x16_bf16 v[20:35], v[238:241], v[48:51], v[20:35]
	s_nop 11
	v_cndmask_b32_e64 v36, 0, v20, s[62:63]
	v_cndmask_b32_e64 v37, v21, 0, s[64:65]
	v_cndmask_b32_e64 v38, 0, v22, s[66:67]
	v_cndmask_b32_e64 v39, 0, v23, s[68:69]
	v_cndmask_b32_e64 v40, 0, v24, s[70:71]
	v_cndmask_b32_e64 v41, 0, v25, s[72:73]
	v_cndmask_b32_e64 v42, 0, v26, s[74:75]
	v_cndmask_b32_e64 v43, 0, v27, s[76:77]
	v_cndmask_b32_e64 v49, 0, v34, s[90:91]
	v_sub_f32_e32 v2, v158, v36
	v_sub_f32_e32 v1, v159, v37
	v_cndmask_b32_e64 v50, 0, v35, s[92:93]
	v_cndmask_b32_e64 v44, 0, v28, s[78:79]
	v_cndmask_b32_e64 v47, 0, v31, s[84:85]
	v_sub_f32_e32 v31, v161, v39
	v_sub_f32_e32 v28, v162, v40
	v_cvt_pk_bf16_f32 v35, v38, v39
	v_cvt_pk_bf16_f32 v34, v36, v37
	v_cndmask_b32_e64 v45, 0, v29, s[80:81]
	v_cndmask_b32_e64 v48, 0, v32, s[86:87]
	v_sub_f32_e32 v32, v160, v38
	v_add_u32_e32 v38, s3, v174
	v_cvt_pk_bf16_f32 v37, v42, v43
	v_cvt_pk_bf16_f32 v36, v40, v41
	v_cndmask_b32_e64 v46, 0, v30, s[82:83]
	v_cndmask_b32_e64 v33, 0, v33, s[88:89]
	ds_write2_b64 v38, v[34:35], v[36:37] offset1:2
	v_sub_f32_e32 v21, v171, v33
	v_cvt_pk_bf16_f32 v34, v44, v45
	v_cvt_pk_bf16_f32 v35, v46, v47
	v_cvt_pk_bf16_f32 v36, v48, v33
	v_cndmask_b32_e64 v33, 0, 1, s[40:41]
	v_sub_f32_e32 v25, v163, v41
	v_sub_f32_e32 v30, v164, v42
	v_sub_f32_e32 v29, v165, v43
	v_sub_f32_e32 v24, v166, v44
	v_sub_f32_e32 v23, v167, v45
	v_sub_f32_e32 v26, v168, v46
	v_sub_f32_e32 v27, v169, v47
	v_sub_f32_e32 v20, v170, v48
	v_sub_f32_e32 v22, v172, v49
	v_sub_f32_e32 v3, v173, v50
	v_cvt_pk_bf16_f32 v37, v49, v50
	v_cmp_ne_u32_e64 s[36:37], 1, v33
	ds_write2_b64 v38, v[34:35], v[36:37] offset0:4 offset1:6
	s_cbranch_vccnz .LBB0_613
	v_cvt_pk_bf16_f32 v33, v32, v31
	v_cvt_pk_bf16_f32 v32, v2, v1
	v_cvt_pk_bf16_f32 v29, v30, v29
	v_cvt_pk_bf16_f32 v28, v28, v25
	v_add_u32_e32 v1, 0, v174
	v_cvt_pk_bf16_f32 v25, v26, v27
	v_cvt_pk_bf16_f32 v24, v24, v23
	v_add_u32_e32 v1, 0x16800, v1
	v_cvt_pk_bf16_f32 v3, v22, v3
	v_cvt_pk_bf16_f32 v2, v20, v21
	ds_write2_b64 v1, v[32:33], v[28:29] offset1:2
	ds_write2_b64 v1, v[24:25], v[2:3] offset0:4 offset1:6
.LBB0_613:
	v_mfma_f32_32x32x16_bf16 v[20:35], v[226:229], v[120:123], 0
	s_and_b64 vcc, exec, s[36:37]
	v_mfma_f32_32x32x16_bf16 v[20:35], v[230:233], v[210:213], v[20:35]
	v_mfma_f32_32x32x16_bf16 v[20:35], v[234:237], v[244:247], v[20:35]
	v_mfma_f32_32x32x16_bf16 v[20:35], v[238:241], v[248:251], v[20:35]
	s_nop 11
	v_cndmask_b32_e64 v36, 0, v20, s[94:95]
	v_cndmask_b32_e64 v37, v21, 0, s[96:97]
	v_cndmask_b32_e64 v38, 0, v22, s[4:5]
	v_cndmask_b32_e64 v39, 0, v23, s[6:7]
	v_cndmask_b32_e64 v40, 0, v24, s[8:9]
	v_cndmask_b32_e64 v41, 0, v25, s[10:11]
	v_cndmask_b32_e64 v42, 0, v26, s[12:13]
	v_cndmask_b32_e64 v43, 0, v27, s[14:15]
	v_cndmask_b32_e64 v49, 0, v34, s[28:29]
	v_sub_f32_e32 v2, v176, v36
	v_sub_f32_e32 v1, v177, v37
	v_cndmask_b32_e64 v50, 0, v35, s[30:31]
	v_cndmask_b32_e64 v44, 0, v28, s[16:17]
	v_cndmask_b32_e64 v47, 0, v31, s[22:23]
	v_sub_f32_e32 v31, v179, v39
	v_sub_f32_e32 v28, v180, v40
	v_cvt_pk_bf16_f32 v35, v38, v39
	v_cvt_pk_bf16_f32 v34, v36, v37
	v_cndmask_b32_e64 v45, 0, v29, s[18:19]
	v_cndmask_b32_e64 v46, 0, v30, s[20:21]
	v_cndmask_b32_e64 v48, 0, v32, s[24:25]
	v_sub_f32_e32 v32, v178, v38
	v_add_u32_e32 v38, s3, v195
	v_cvt_pk_bf16_f32 v37, v42, v43
	v_cvt_pk_bf16_f32 v36, v40, v41
	v_cndmask_b32_e64 v33, 0, v33, s[26:27]
	ds_write2_b64 v38, v[34:35], v[36:37] offset1:2
	v_sub_f32_e32 v21, v189, v33
	v_cvt_pk_bf16_f32 v35, v46, v47
	v_cvt_pk_bf16_f32 v34, v44, v45
	v_sub_f32_e32 v25, v181, v41
	v_sub_f32_e32 v30, v182, v42
	v_sub_f32_e32 v29, v183, v43
	v_sub_f32_e32 v24, v184, v44
	v_sub_f32_e32 v23, v185, v45
	v_sub_f32_e32 v26, v186, v46
	v_sub_f32_e32 v27, v187, v47
	v_sub_f32_e32 v20, v188, v48
	v_sub_f32_e32 v22, v190, v49
	v_sub_f32_e32 v3, v191, v50
	v_cvt_pk_bf16_f32 v37, v49, v50
	v_cvt_pk_bf16_f32 v36, v48, v33
	ds_write2_b64 v38, v[34:35], v[36:37] offset0:4 offset1:6
	s_cbranch_vccnz .LBB0_615
	v_cvt_pk_bf16_f32 v33, v32, v31
	v_cvt_pk_bf16_f32 v32, v2, v1
	v_cvt_pk_bf16_f32 v29, v30, v29
	v_cvt_pk_bf16_f32 v28, v28, v25
	v_add_u32_e32 v1, 0, v195
	v_cvt_pk_bf16_f32 v25, v26, v27
	v_cvt_pk_bf16_f32 v24, v24, v23
	v_add_u32_e32 v1, 0x16800, v1
	v_cvt_pk_bf16_f32 v3, v22, v3
	v_cvt_pk_bf16_f32 v2, v20, v21
	ds_write2_b64 v1, v[32:33], v[28:29] offset1:2
	ds_write2_b64 v1, v[24:25], v[2:3] offset0:4 offset1:6
